# baseline (speedup 1.0000x reference)
; __device__ void phase_norm_mod(const Params& p, const float* __restrict__ xin, const float* __restrict__ g, const float* __restrict__ sh,
;                                const float* __restrict__ sc) {
;     ...
;     for (int r0 = (gw >> 1) * 2; r0 < SEQ; r0 += GW) {
;         const size_t row = (size_t)b * SEQ + r0;
;         const float4* xr = reinterpret_cast<const float4*>(xin + row * D);
;         float4 v0[4], v1[4];
; #pragma unroll
;         for (int i = 0; i < 4; ++i) { v0[i] = xr[lane + 64 * i]; v1[i] = xr[256 + lane + 64 * i]; }
;         float ss0 = 0.f, ss1 = 0.f;
; #pragma unroll
;         for (int i = 0; i < 4; ++i) { ss0 += sumsq4(v0[i]); ss1 += sumsq4(v1[i]); }
;         ss0 = wave_sum(ss0); ss1 = wave_sum(ss1);
;         const float rs0 = rsqrtf(ss0 * (1.f / D) + EPS), rs1 = rsqrtf(ss1 * (1.f / D) + EPS);
.LBB0_527:
	global_load_dwordx4 v[50:53], v[40:41], off offset:-4096
	global_load_dwordx4 v[54:57], v[40:41], off offset:-3072
	global_load_dwordx4 v[62:65], v[40:41], off offset:-2048
	global_load_dwordx4 v[70:73], v[40:41], off offset:-1024
	global_load_dwordx4 v[18:21], v[40:41], off
	global_load_dwordx4 v[58:61], v[40:41], off offset:1024
	global_load_dwordx4 v[66:69], v[40:41], off offset:2048
	global_load_dwordx4 v[74:77], v[40:41], off offset:3072
	v_add_u32_e32 v22, s6, v22
	v_lshl_add_u64 v[40:41], v[40:41], 0, s[8:9]
	v_and_b32_e32 v89, 63, v189
	v_mul_u32_u24_e32 v89, 0x70, v89
	v_add_co_u32_e32 v90, vcc, v40, v89
	v_addc_co_u32_e32 v91, vcc, 0, v41, vcc
	s_movk_i32 s2, 0x3fff
	v_cmp_ge_i32_e32 vcc, s2, v22
	s_and_saveexec_b64 s[2:3], vcc
	global_load_dword v88, v[90:91], off offset:-4096
	s_mov_b64 exec, s[2:3]
	s_waitcnt vmcnt(8)
	v_pk_mul_f32 v[80:81], v[50:51], v[50:51]
	v_pk_mul_f32 v[84:85], v[52:53], v[52:53]
	s_waitcnt vmcnt(7)
	v_pk_fma_f32 v[80:81], v[54:55], v[54:55], v[80:81]
	v_pk_fma_f32 v[84:85], v[56:57], v[56:57], v[84:85]
	s_waitcnt vmcnt(6)
	v_pk_fma_f32 v[80:81], v[62:63], v[62:63], v[80:81]
	v_pk_fma_f32 v[84:85], v[64:65], v[64:65], v[84:85]
	s_waitcnt vmcnt(5)
	v_pk_fma_f32 v[80:81], v[70:71], v[70:71], v[80:81]
	v_pk_fma_f32 v[84:85], v[72:73], v[72:73], v[84:85]
	s_waitcnt vmcnt(4)
	v_pk_mul_f32 v[82:83], v[18:19], v[18:19]
	v_pk_mul_f32 v[86:87], v[20:21], v[20:21]
	s_waitcnt vmcnt(3)
	v_pk_fma_f32 v[82:83], v[58:59], v[58:59], v[82:83]
	v_pk_fma_f32 v[86:87], v[60:61], v[60:61], v[86:87]
	s_waitcnt vmcnt(2)
	v_pk_fma_f32 v[82:83], v[66:67], v[66:67], v[82:83]
	v_pk_fma_f32 v[86:87], v[68:69], v[68:69], v[86:87]
	s_waitcnt vmcnt(1)
	v_pk_fma_f32 v[82:83], v[74:75], v[74:75], v[82:83]
	v_pk_fma_f32 v[86:87], v[76:77], v[76:77], v[86:87]
	v_pk_add_f32 v[80:81], v[80:81], v[84:85]
	v_pk_add_f32 v[82:83], v[82:83], v[86:87]
	s_nop 0
	v_add_f32_e32 v79, v80, v81
	v_add_f32_e32 v78, v82, v83
	ds_bpermute_b32 v81, v44, v79
	ds_bpermute_b32 v80, v44, v78
	s_waitcnt lgkmcnt(0)
	v_pk_add_f32 v[78:79], v[78:79], v[80:81]
	ds_bpermute_b32 v81, v45, v79
	ds_bpermute_b32 v80, v45, v78
	s_waitcnt lgkmcnt(0)
	v_pk_add_f32 v[78:79], v[78:79], v[80:81]
	ds_bpermute_b32 v81, v46, v79
	ds_bpermute_b32 v80, v46, v78
	s_waitcnt lgkmcnt(0)
	v_pk_add_f32 v[78:79], v[78:79], v[80:81]
	ds_bpermute_b32 v81, v47, v79
	ds_bpermute_b32 v80, v47, v78
	s_waitcnt lgkmcnt(0)
	v_pk_add_f32 v[78:79], v[78:79], v[80:81]
	ds_bpermute_b32 v81, v48, v79
	ds_bpermute_b32 v80, v48, v78
	s_waitcnt lgkmcnt(0)
	v_pk_add_f32 v[78:79], v[78:79], v[80:81]
	ds_bpermute_b32 v81, v49, v79
	ds_bpermute_b32 v80, v49, v78
	s_waitcnt lgkmcnt(0)
	v_pk_add_f32 v[78:79], v[78:79], v[80:81]
	s_nop 0
	v_pk_fma_f32 v[78:79], v[78:79], s[96:97], v[188:189] op_sel_hi:[1,0,0]
	s_nop 0
	v_mul_f32_e32 v0, 0x4b800000, v79
	v_cmp_gt_f32_e64 s[2:3], s74, v79
	v_cmp_gt_f32_e32 vcc, s74, v78
	s_nop 0
	v_cndmask_b32_e64 v0, v79, v0, s[2:3]
	v_rsq_f32_e32 v0, v0
	s_nop 0
	v_mul_f32_e32 v23, 0x45800000, v0
	v_cndmask_b32_e64 v0, v0, v23, s[2:3]
	v_pk_mul_f32 v[50:51], v[50:51], v[0:1] op_sel_hi:[1,0]
	v_pk_mul_f32 v[52:53], v[52:53], v[0:1] op_sel_hi:[1,0]
	v_pk_fma_f32 v[50:51], v[24:25], v[50:51], v[2:3]
	v_pk_fma_f32 v[52:53], v[26:27], v[52:53], v[4:5]
	v_cvt_pk_bf16_f32 v50, v50, v51
	v_cvt_pk_bf16_f32 v51, v52, v53
	global_store_dwordx2 v[42:43], v[50:51], off offset:-2048
	v_pk_mul_f32 v[50:51], v[54:55], v[0:1] op_sel_hi:[1,0]
	v_pk_mul_f32 v[52:53], v[56:57], v[0:1] op_sel_hi:[1,0]
	v_pk_fma_f32 v[50:51], v[28:29], v[50:51], v[6:7]
	v_pk_fma_f32 v[52:53], v[30:31], v[52:53], v[8:9]
	v_cvt_pk_bf16_f32 v50, v50, v51
	v_cvt_pk_bf16_f32 v51, v52, v53
	global_store_dwordx2 v[42:43], v[50:51], off offset:-1536
	v_pk_mul_f32 v[50:51], v[62:63], v[0:1] op_sel_hi:[1,0]
	v_pk_mul_f32 v[52:53], v[64:65], v[0:1] op_sel_hi:[1,0]
	v_pk_fma_f32 v[50:51], v[32:33], v[50:51], v[10:11]
	v_pk_fma_f32 v[52:53], v[34:35], v[52:53], v[12:13]
	v_cvt_pk_bf16_f32 v50, v50, v51
	v_cvt_pk_bf16_f32 v51, v52, v53
	global_store_dwordx2 v[42:43], v[50:51], off offset:-1024
	v_pk_mul_f32 v[50:51], v[70:71], v[0:1] op_sel_hi:[1,0]
	v_pk_mul_f32 v[52:53], v[72:73], v[0:1] op_sel_hi:[1,0]
	v_mul_f32_e32 v0, 0x4b800000, v78
	v_cndmask_b32_e32 v0, v78, v0, vcc
	v_rsq_f32_e32 v0, v0
	v_pk_fma_f32 v[50:51], v[36:37], v[50:51], v[14:15]
	v_pk_fma_f32 v[52:53], v[38:39], v[52:53], v[16:17]
	s_movk_i32 s2, 0x3fff
	v_mul_f32_e32 v23, 0x45800000, v0
	v_cndmask_b32_e32 v0, v0, v23, vcc
	v_pk_mul_f32 v[18:19], v[18:19], v[0:1] op_sel_hi:[1,0]
	v_pk_mul_f32 v[20:21], v[20:21], v[0:1] op_sel_hi:[1,0]
	v_pk_fma_f32 v[18:19], v[24:25], v[18:19], v[2:3]
	v_pk_fma_f32 v[20:21], v[26:27], v[20:21], v[4:5]
	v_cvt_pk_bf16_f32 v18, v18, v19
	v_cvt_pk_bf16_f32 v19, v20, v21
	global_store_dwordx2 v[42:43], v[18:19], off
	v_pk_mul_f32 v[18:19], v[58:59], v[0:1] op_sel_hi:[1,0]
	v_pk_mul_f32 v[20:21], v[60:61], v[0:1] op_sel_hi:[1,0]
	v_pk_fma_f32 v[18:19], v[28:29], v[18:19], v[6:7]
	v_pk_fma_f32 v[20:21], v[30:31], v[20:21], v[8:9]
	v_cvt_pk_bf16_f32 v18, v18, v19
	v_cvt_pk_bf16_f32 v19, v20, v21
	global_store_dwordx2 v[42:43], v[18:19], off offset:512
	v_pk_mul_f32 v[18:19], v[66:67], v[0:1] op_sel_hi:[1,0]
	v_pk_mul_f32 v[20:21], v[68:69], v[0:1] op_sel_hi:[1,0]
	v_pk_fma_f32 v[18:19], v[32:33], v[18:19], v[10:11]
	v_pk_fma_f32 v[20:21], v[34:35], v[20:21], v[12:13]
	v_cvt_pk_bf16_f32 v18, v18, v19
	v_cvt_pk_bf16_f32 v19, v20, v21
	global_store_dwordx2 v[42:43], v[18:19], off offset:1024
	v_pk_mul_f32 v[18:19], v[74:75], v[0:1] op_sel_hi:[1,0]
	v_pk_mul_f32 v[20:21], v[76:77], v[0:1] op_sel_hi:[1,0]
	v_cvt_pk_bf16_f32 v50, v50, v51
	v_cvt_pk_bf16_f32 v51, v52, v53
	v_pk_fma_f32 v[18:19], v[36:37], v[18:19], v[14:15]
	v_pk_fma_f32 v[20:21], v[38:39], v[20:21], v[16:17]
	v_cmp_lt_i32_e32 vcc, s2, v22
	v_cvt_pk_bf16_f32 v18, v18, v19
	v_cvt_pk_bf16_f32 v19, v20, v21
	global_store_dwordx2 v[42:43], v[50:51], off offset:-512
	global_store_dwordx2 v[42:43], v[18:19], off offset:1536
	v_lshl_add_u64 v[42:43], v[42:43], 0, s[10:11]
	s_or_b64 s[12:13], vcc, s[12:13]
	s_andn2_b64 exec, exec, s[12:13]
	s_cbranch_execnz .LBB0_527
